# GEMM K-loops: back-edge rotation, next iteration's scalar address set-up moved in front of the previous iteration's last barrier
# baseline (speedup 1.0000x reference)
; #define PG8_STAGE(bufoff, gbase, voff) do { _Pragma("unroll") for (int _i = 0; _i < 2; ++_i) \
;         __builtin_amdgcn_global_load_lds((const unsigned*)((const char*)(gbase) + (voff)[_i]), (PG8_LAS unsigned*)(lds + (bufoff) + ldsw + _i * 8192), 16, 0, 0); } while (0)
; #define PG8_LDA(dst, b, h) do { _Pragma("unroll") for (int m = 0; m < 4; ++m) _Pragma("unroll") for (int k = 0; k < 2; ++k) dst[m][k] = *(const PG8_LAS bf16x8*)(lds + PG8_SA(b, h) + aoff + m * 2048 + k * 1024); } while (0)
; #define PG8_LDB(dst, b, h) do { _Pragma("unroll") for (int n = 0; n < 2; ++n) _Pragma("unroll") for (int k = 0; k < 2; ++k) dst[n][k] = *(const PG8_LAS bf16x8*)(lds + PG8_SB(b, h) + boff + n * 2048 + k * 1024); } while (0)
; #define PG8_MMA(ai, bj, At, Bt) do { __builtin_amdgcn_s_setprio(1); _Pragma("unroll") for (int m = 0; m < 4; ++m) _Pragma("unroll") for (int n = 0; n < 2; ++n) _Pragma("unroll") for (int k = 0; k < 2; ++k) \
;         acc[ai][bj][m][n] = __builtin_amdgcn_mfma_f32_16x16x32_bf16(Bt[n][k], At[m][k], acc[ai][bj][m][n], 0, 0, 0); __builtin_amdgcn_s_setprio(0); } while (0)
; #define PG8_WAIT_V(n) asm volatile("s_waitcnt vmcnt(" #n ")" ::: "memory")
; #define PG8_WAIT_L(n) asm volatile("s_waitcnt lgkmcnt(" #n ")" ::: "memory")
; #define PG8_BAR __builtin_amdgcn_s_barrier()
; #define PG8_SCHED __builtin_amdgcn_sched_barrier(0)
; template <class Epi, class Sched, bool ALIGN_EPI = false, bool SP2 = false>
; __device__ __forceinline__ void gemm_phase(PG8_LAS unsigned char* lds, const Gemm g, const Sched& S, const Epi& E, int tid_in) {
;     ...
;             PG8_LDB(B0, 0, 0); PG8_LDB(B1, 0, 1); PG8_SCHED; PG8_LDA(At, 0, 0); PG8_STAGE(PG8_SA(1, 1), a1 + hstepA, voffA);
;             PG8_WAIT_V(8); PG8_WAIT_L(0); PG8_BAR; PG8_MMA(0, 0, At, B0); PG8_MMA(0, 1, At, B1); PG8_BAR; PG8_SCHED;
;             PG8_LDA(At, 0, 1); PG8_STAGE(PG8_SB(0, 0), b2, voffB); PG8_STAGE(PG8_SB(0, 1), b2 + hstep, voffB); PG8_STAGE(PG8_SA(0, 0), a2, voffA);
.Lrot0_body:
	s_add_i32 s81, 0, 0x10000
	v_add_u32_e32 v0, s81, v205
	s_add_i32 s82, 0, 0x14000
	ds_read_b128 v[134:137], v0
	ds_read_b128 v[138:141], v0 offset:1024
	ds_read_b128 v[142:145], v0 offset:2048
	ds_read_b128 v[146:149], v0 offset:3072
	v_add_u32_e32 v0, s82, v205
	ds_read_b128 v[150:153], v0
	ds_read_b128 v[154:157], v0 offset:1024
	ds_read_b128 v[158:161], v0 offset:2048
	ds_read_b128 v[162:165], v0 offset:3072
	s_add_u32 s78, s27, s0
	s_addc_u32 s79, s79, s1
	v_lshl_add_u64 v[214:215], v[130:131], 0, s[78:79]
	s_add_i32 m0, s58, 0xc000
	ds_read_b128 v[166:169], v246
	ds_read_b128 v[170:173], v246 offset:1024
	ds_read_b128 v[174:177], v246 offset:2048
	ds_read_b128 v[178:181], v246 offset:3072
	ds_read_b128 v[182:185], v246 offset:4096
	ds_read_b128 v[186:189], v246 offset:5120
	ds_read_b128 v[190:193], v246 offset:6144
	ds_read_b128 v[210:213], v246 offset:7168
	global_load_lds_dwordx4 v[214:215], off
	v_lshl_add_u64 v[214:215], v[132:133], 0, s[78:79]
	s_add_i32 m0, s58, 0xe000
	s_nop 0
	global_load_lds_dwordx4 v[214:215], off
	s_waitcnt vmcnt(8)
	s_waitcnt lgkmcnt(0)
	s_barrier
	s_setprio 1
	s_waitcnt lgkmcnt(0)
	v_mfma_f32_16x16x32_bf16 v[122:125], v[134:137], v[166:169], v[122:125]
	v_mfma_f32_16x16x32_bf16 v[114:117], v[142:145], v[166:169], v[114:117]
	v_mfma_f32_16x16x32_bf16 v[106:109], v[134:137], v[174:177], v[106:109]
	v_mfma_f32_16x16x32_bf16 v[98:101], v[142:145], v[174:177], v[98:101]
	v_mfma_f32_16x16x32_bf16 v[90:93], v[134:137], v[182:185], v[90:93]
	v_mfma_f32_16x16x32_bf16 v[82:85], v[142:145], v[182:185], v[82:85]
	v_mfma_f32_16x16x32_bf16 v[74:77], v[134:137], v[190:193], v[74:77]
	v_mfma_f32_16x16x32_bf16 v[66:69], v[142:145], v[190:193], v[66:69]
	v_mfma_f32_16x16x32_bf16 v[122:125], v[138:141], v[170:173], v[122:125]
	v_mfma_f32_16x16x32_bf16 v[114:117], v[146:149], v[170:173], v[114:117]
	v_mfma_f32_16x16x32_bf16 v[106:109], v[138:141], v[178:181], v[106:109]
	v_mfma_f32_16x16x32_bf16 v[98:101], v[146:149], v[178:181], v[98:101]
	v_mfma_f32_16x16x32_bf16 v[90:93], v[138:141], v[186:189], v[90:93]
	v_mfma_f32_16x16x32_bf16 v[82:85], v[146:149], v[186:189], v[82:85]
	v_mfma_f32_16x16x32_bf16 v[74:77], v[138:141], v[210:213], v[74:77]
	v_mfma_f32_16x16x32_bf16 v[66:69], v[146:149], v[210:213], v[66:69]
	s_setprio 0
	s_setprio 1
	v_mfma_f32_16x16x32_bf16 v[126:129], v[150:153], v[166:169], v[126:129]
	v_mfma_f32_16x16x32_bf16 v[118:121], v[158:161], v[166:169], v[118:121]
	v_mfma_f32_16x16x32_bf16 v[110:113], v[150:153], v[174:177], v[110:113]
	v_mfma_f32_16x16x32_bf16 v[102:105], v[158:161], v[174:177], v[102:105]
	v_mfma_f32_16x16x32_bf16 v[94:97], v[150:153], v[182:185], v[94:97]
	v_mfma_f32_16x16x32_bf16 v[86:89], v[158:161], v[182:185], v[86:89]
	v_mfma_f32_16x16x32_bf16 v[78:81], v[150:153], v[190:193], v[78:81]
	v_mfma_f32_16x16x32_bf16 v[70:73], v[158:161], v[190:193], v[70:73]
	v_mfma_f32_16x16x32_bf16 v[126:129], v[154:157], v[170:173], v[126:129]
	v_mfma_f32_16x16x32_bf16 v[118:121], v[162:165], v[170:173], v[118:121]
	v_mfma_f32_16x16x32_bf16 v[110:113], v[154:157], v[178:181], v[110:113]
	v_mfma_f32_16x16x32_bf16 v[102:105], v[162:165], v[178:181], v[102:105]
	v_mfma_f32_16x16x32_bf16 v[94:97], v[154:157], v[186:189], v[94:97]
	v_mfma_f32_16x16x32_bf16 v[86:89], v[162:165], v[186:189], v[86:89]
	v_mfma_f32_16x16x32_bf16 v[78:81], v[154:157], v[210:213], v[78:81]
	v_mfma_f32_16x16x32_bf16 v[70:73], v[162:165], v[210:213], v[70:73]
	s_setprio 0
	s_barrier
	s_add_i32 s27, s81, s55
	v_lshl_add_u64 v[214:215], s[46:47], 0, v[202:203]
	s_mov_b32 m0, s27
	ds_read_b128 v[166:169], v246 offset:16384
	ds_read_b128 v[170:173], v246 offset:17408
	ds_read_b128 v[174:177], v246 offset:18432
	ds_read_b128 v[178:181], v246 offset:19456
	ds_read_b128 v[182:185], v246 offset:20480
	ds_read_b128 v[186:189], v246 offset:21504
	ds_read_b128 v[190:193], v246 offset:22528
	ds_read_b128 v[210:213], v246 offset:23552
	global_load_lds_dwordx4 v[214:215], off
	s_add_i32 m0, s27, 0x2000
	v_lshl_add_u64 v[216:217], s[46:47], 0, v[198:199]
	s_add_u32 s46, s46, s52
	s_addc_u32 s47, s47, 0
	s_add_i32 s27, s82, s55
	global_load_lds_dwordx4 v[216:217], off
	v_lshl_add_u64 v[218:219], s[46:47], 0, v[202:203]
	s_mov_b32 m0, s27
	v_lshl_add_u64 v[220:221], s[46:47], 0, v[198:199]
	global_load_lds_dwordx4 v[218:219], off
	s_add_i32 m0, s27, 0x2000
	v_lshl_add_u64 v[234:235], s[44:45], 0, v[200:201]
	global_load_lds_dwordx4 v[220:221], off
	s_mov_b32 m0, s58
	s_nop 0
	global_load_lds_dwordx4 v[234:235], off
	v_lshl_add_u64 v[234:235], s[44:45], 0, v[196:197]
	s_mov_b32 m0, s59
	s_nop 0
	global_load_lds_dwordx4 v[234:235], off
	s_waitcnt vmcnt(8)
	s_waitcnt lgkmcnt(0)
	s_barrier
; #define PG8_STAGE(bufoff, gbase, voff) do { _Pragma("unroll") for (int _i = 0; _i < 2; ++_i) \
;         __builtin_amdgcn_global_load_lds((const unsigned*)((const char*)(gbase) + (voff)[_i]), (PG8_LAS unsigned*)(lds + (bufoff) + ldsw + _i * 8192), 16, 0, 0); } while (0)
; #define PG8_LDA(dst, b, h) do { _Pragma("unroll") for (int m = 0; m < 4; ++m) _Pragma("unroll") for (int k = 0; k < 2; ++k) dst[m][k] = *(const PG8_LAS bf16x8*)(lds + PG8_SA(b, h) + aoff + m * 2048 + k * 1024); } while (0)
; #define PG8_LDB(dst, b, h) do { _Pragma("unroll") for (int n = 0; n < 2; ++n) _Pragma("unroll") for (int k = 0; k < 2; ++k) dst[n][k] = *(const PG8_LAS bf16x8*)(lds + PG8_SB(b, h) + boff + n * 2048 + k * 1024); } while (0)
; #define PG8_MMA(ai, bj, At, Bt) do { __builtin_amdgcn_s_setprio(1); _Pragma("unroll") for (int m = 0; m < 4; ++m) _Pragma("unroll") for (int n = 0; n < 2; ++n) _Pragma("unroll") for (int k = 0; k < 2; ++k) \
;         acc[ai][bj][m][n] = __builtin_amdgcn_mfma_f32_16x16x32_bf16(Bt[n][k], At[m][k], acc[ai][bj][m][n], 0, 0, 0); __builtin_amdgcn_s_setprio(0); } while (0)
; #define PG8_WAIT_V(n) asm volatile("s_waitcnt vmcnt(" #n ")" ::: "memory")
; #define PG8_WAIT_L(n) asm volatile("s_waitcnt lgkmcnt(" #n ")" ::: "memory")
; #define PG8_BAR __builtin_amdgcn_s_barrier()
; #define PG8_SCHED __builtin_amdgcn_sched_barrier(0)
; template <class Epi, class Sched, bool ALIGN_EPI = false, bool SP2 = false>
; __device__ __forceinline__ void gemm_phase(PG8_LAS unsigned char* lds, const Gemm g, const Sched& S, const Epi& E, int tid_in) {
;     ...
;             PG8_WAIT_V(8); PG8_WAIT_L(0); PG8_BAR; PG8_MMA(1, 0, At, B0); PG8_MMA(1, 1, At, B1); PG8_BAR; PG8_SCHED;
;             PG8_LDB(B0, 1, 0); PG8_LDB(B1, 1, 1); PG8_SCHED; PG8_LDA(At, 1, 0); PG8_STAGE(PG8_SA(0, 1), a2 + hstepA, voffA);
;             PG8_WAIT_V(8); PG8_WAIT_L(0); PG8_BAR; PG8_MMA(0, 0, At, B0); PG8_MMA(0, 1, At, B1); PG8_BAR; PG8_SCHED;
	s_setprio 1
	s_waitcnt lgkmcnt(0)
	v_mfma_f32_16x16x32_bf16 v[58:61], v[134:137], v[166:169], v[58:61]
	v_mfma_f32_16x16x32_bf16 v[50:53], v[142:145], v[166:169], v[50:53]
	v_mfma_f32_16x16x32_bf16 v[42:45], v[134:137], v[174:177], v[42:45]
	v_mfma_f32_16x16x32_bf16 v[34:37], v[142:145], v[174:177], v[34:37]
	v_mfma_f32_16x16x32_bf16 v[26:29], v[134:137], v[182:185], v[26:29]
	v_mfma_f32_16x16x32_bf16 v[18:21], v[142:145], v[182:185], v[18:21]
	v_mfma_f32_16x16x32_bf16 v[10:13], v[134:137], v[190:193], v[10:13]
	v_mfma_f32_16x16x32_bf16 v[6:9], v[142:145], v[190:193], v[6:9]
	v_mfma_f32_16x16x32_bf16 v[58:61], v[138:141], v[170:173], v[58:61]
	v_mfma_f32_16x16x32_bf16 v[50:53], v[146:149], v[170:173], v[50:53]
	v_mfma_f32_16x16x32_bf16 v[42:45], v[138:141], v[178:181], v[42:45]
	v_mfma_f32_16x16x32_bf16 v[34:37], v[146:149], v[178:181], v[34:37]
	v_mfma_f32_16x16x32_bf16 v[26:29], v[138:141], v[186:189], v[26:29]
	v_mfma_f32_16x16x32_bf16 v[18:21], v[146:149], v[186:189], v[18:21]
	v_mfma_f32_16x16x32_bf16 v[10:13], v[138:141], v[210:213], v[10:13]
	v_mfma_f32_16x16x32_bf16 v[6:9], v[146:149], v[210:213], v[6:9]
	s_setprio 0
	s_setprio 1
	v_mfma_f32_16x16x32_bf16 v[62:65], v[150:153], v[166:169], v[62:65]
	v_mfma_f32_16x16x32_bf16 v[54:57], v[158:161], v[166:169], v[54:57]
	v_mfma_f32_16x16x32_bf16 v[46:49], v[150:153], v[174:177], v[46:49]
	v_mfma_f32_16x16x32_bf16 v[38:41], v[158:161], v[174:177], v[38:41]
	v_mfma_f32_16x16x32_bf16 v[30:33], v[150:153], v[182:185], v[30:33]
	v_mfma_f32_16x16x32_bf16 v[22:25], v[158:161], v[182:185], v[22:25]
	v_mfma_f32_16x16x32_bf16 v[14:17], v[150:153], v[190:193], v[14:17]
	v_mfma_f32_16x16x32_bf16 v[2:5], v[158:161], v[190:193], v[2:5]
	v_mfma_f32_16x16x32_bf16 v[62:65], v[154:157], v[170:173], v[62:65]
	v_mfma_f32_16x16x32_bf16 v[54:57], v[162:165], v[170:173], v[54:57]
	v_mfma_f32_16x16x32_bf16 v[46:49], v[154:157], v[178:181], v[46:49]
	v_mfma_f32_16x16x32_bf16 v[38:41], v[162:165], v[178:181], v[38:41]
	v_mfma_f32_16x16x32_bf16 v[30:33], v[154:157], v[186:189], v[30:33]
	v_mfma_f32_16x16x32_bf16 v[22:25], v[162:165], v[186:189], v[22:25]
	v_mfma_f32_16x16x32_bf16 v[14:17], v[154:157], v[210:213], v[14:17]
	v_mfma_f32_16x16x32_bf16 v[2:5], v[162:165], v[210:213], v[2:5]
	s_setprio 0
	s_barrier
	s_add_i32 s27, 0, 0x18000
	v_add_u32_e32 v0, s27, v205
	s_add_i32 s46, 0, 0x1c000
	ds_read_b128 v[134:137], v0
	ds_read_b128 v[138:141], v0 offset:1024
	ds_read_b128 v[142:145], v0 offset:2048
	ds_read_b128 v[146:149], v0 offset:3072
	v_add_u32_e32 v0, s46, v205
	ds_read_b128 v[150:153], v0
	ds_read_b128 v[154:157], v0 offset:1024
	ds_read_b128 v[158:161], v0 offset:2048
	ds_read_b128 v[162:165], v0 offset:3072
	s_add_u32 s44, s44, s28
	s_addc_u32 s45, s45, 0
	s_mov_b32 m0, s60
	v_lshl_add_u64 v[234:235], s[44:45], 0, v[200:201]
	ds_read_b128 v[166:169], v246 offset:32768
	ds_read_b128 v[170:173], v246 offset:33792
	ds_read_b128 v[174:177], v246 offset:34816
	ds_read_b128 v[178:181], v246 offset:35840
	ds_read_b128 v[182:185], v246 offset:36864
	ds_read_b128 v[186:189], v246 offset:37888
	ds_read_b128 v[190:193], v246 offset:38912
	ds_read_b128 v[210:213], v246 offset:39936
	global_load_lds_dwordx4 v[234:235], off
	v_lshl_add_u64 v[234:235], s[44:45], 0, v[196:197]
	s_mov_b32 m0, s61
	s_nop 0
	global_load_lds_dwordx4 v[234:235], off
	s_waitcnt vmcnt(8)
	s_waitcnt lgkmcnt(0)
	s_barrier
	s_setprio 1
	s_waitcnt lgkmcnt(0)
	v_mfma_f32_16x16x32_bf16 v[122:125], v[134:137], v[166:169], v[122:125]
	v_mfma_f32_16x16x32_bf16 v[114:117], v[142:145], v[166:169], v[114:117]
	v_mfma_f32_16x16x32_bf16 v[106:109], v[134:137], v[174:177], v[106:109]
	v_mfma_f32_16x16x32_bf16 v[98:101], v[142:145], v[174:177], v[98:101]
	v_mfma_f32_16x16x32_bf16 v[90:93], v[134:137], v[182:185], v[90:93]
	v_mfma_f32_16x16x32_bf16 v[82:85], v[142:145], v[182:185], v[82:85]
	v_mfma_f32_16x16x32_bf16 v[74:77], v[134:137], v[190:193], v[74:77]
	v_mfma_f32_16x16x32_bf16 v[66:69], v[142:145], v[190:193], v[66:69]
	v_mfma_f32_16x16x32_bf16 v[122:125], v[138:141], v[170:173], v[122:125]
	v_mfma_f32_16x16x32_bf16 v[114:117], v[146:149], v[170:173], v[114:117]
	v_mfma_f32_16x16x32_bf16 v[106:109], v[138:141], v[178:181], v[106:109]
	v_mfma_f32_16x16x32_bf16 v[98:101], v[146:149], v[178:181], v[98:101]
	v_mfma_f32_16x16x32_bf16 v[90:93], v[138:141], v[186:189], v[90:93]
	v_mfma_f32_16x16x32_bf16 v[82:85], v[146:149], v[186:189], v[82:85]
	v_mfma_f32_16x16x32_bf16 v[74:77], v[138:141], v[210:213], v[74:77]
	v_mfma_f32_16x16x32_bf16 v[66:69], v[146:149], v[210:213], v[66:69]
	s_setprio 0
	s_setprio 1
	v_mfma_f32_16x16x32_bf16 v[126:129], v[150:153], v[166:169], v[126:129]
	v_mfma_f32_16x16x32_bf16 v[118:121], v[158:161], v[166:169], v[118:121]
	v_mfma_f32_16x16x32_bf16 v[110:113], v[150:153], v[174:177], v[110:113]
	v_mfma_f32_16x16x32_bf16 v[102:105], v[158:161], v[174:177], v[102:105]
	v_mfma_f32_16x16x32_bf16 v[94:97], v[150:153], v[182:185], v[94:97]
	v_mfma_f32_16x16x32_bf16 v[86:89], v[158:161], v[182:185], v[86:89]
	v_mfma_f32_16x16x32_bf16 v[78:81], v[150:153], v[190:193], v[78:81]
	v_mfma_f32_16x16x32_bf16 v[70:73], v[158:161], v[190:193], v[70:73]
	v_mfma_f32_16x16x32_bf16 v[126:129], v[154:157], v[170:173], v[126:129]
	v_mfma_f32_16x16x32_bf16 v[118:121], v[162:165], v[170:173], v[118:121]
	v_mfma_f32_16x16x32_bf16 v[110:113], v[154:157], v[178:181], v[110:113]
	v_mfma_f32_16x16x32_bf16 v[102:105], v[162:165], v[178:181], v[102:105]
	v_mfma_f32_16x16x32_bf16 v[94:97], v[154:157], v[186:189], v[94:97]
	v_mfma_f32_16x16x32_bf16 v[86:89], v[162:165], v[186:189], v[86:89]
	v_mfma_f32_16x16x32_bf16 v[78:81], v[154:157], v[210:213], v[78:81]
	v_mfma_f32_16x16x32_bf16 v[70:73], v[162:165], v[210:213], v[70:73]
	s_setprio 0
	s_barrier
; #define PG8_STAGE(bufoff, gbase, voff) do { _Pragma("unroll") for (int _i = 0; _i < 2; ++_i) \
;         __builtin_amdgcn_global_load_lds((const unsigned*)((const char*)(gbase) + (voff)[_i]), (PG8_LAS unsigned*)(lds + (bufoff) + ldsw + _i * 8192), 16, 0, 0); } while (0)
; #define PG8_LDA(dst, b, h) do { _Pragma("unroll") for (int m = 0; m < 4; ++m) _Pragma("unroll") for (int k = 0; k < 2; ++k) dst[m][k] = *(const PG8_LAS bf16x8*)(lds + PG8_SA(b, h) + aoff + m * 2048 + k * 1024); } while (0)
; #define PG8_MMA(ai, bj, At, Bt) do { __builtin_amdgcn_s_setprio(1); _Pragma("unroll") for (int m = 0; m < 4; ++m) _Pragma("unroll") for (int n = 0; n < 2; ++n) _Pragma("unroll") for (int k = 0; k < 2; ++k) \
;         acc[ai][bj][m][n] = __builtin_amdgcn_mfma_f32_16x16x32_bf16(Bt[n][k], At[m][k], acc[ai][bj][m][n], 0, 0, 0); __builtin_amdgcn_s_setprio(0); } while (0)
; #define PG8_WAIT_V(n) asm volatile("s_waitcnt vmcnt(" #n ")" ::: "memory")
; #define PG8_WAIT_L(n) asm volatile("s_waitcnt lgkmcnt(" #n ")" ::: "memory")
; #define PG8_BAR __builtin_amdgcn_s_barrier()
; #define PG8_SCHED __builtin_amdgcn_sched_barrier(0)
; template <class Epi, class Sched, bool ALIGN_EPI = false, bool SP2 = false>
; __device__ __forceinline__ void gemm_phase(PG8_LAS unsigned char* lds, const Gemm g, const Sched& S, const Epi& E, int tid_in) {
;     ...
;         for (int t = 0; t < ntc; t += 2) {
;             const bool last = (t == ntc - 2);
;             const char* a1 = PG8_KA(cA, t + 1);
;             const char* a2 = last ? nA : PG8_KA(cA, t + 2); const char* b2 = last ? nB : cB + (size_t)(t + 2) * kstep;
;             const char* a3 = last ? PG8_KA(nA, 1) : PG8_KA(cA, t + 3); const char* b3 = b2 + kstep;
;     ...
;             PG8_LDA(At, 1, 1); PG8_STAGE(PG8_SB(1, 0), b3, voffB); PG8_STAGE(PG8_SB(1, 1), b3 + hstep, voffB); PG8_STAGE(PG8_SA(1, 0), a3, voffA);
;             PG8_WAIT_V(8); PG8_WAIT_L(0); PG8_BAR; PG8_MMA(1, 0, At, B0); PG8_MMA(1, 1, At, B1); PG8_BAR; PG8_SCHED;
	s_add_i32 s27, s27, s55
	v_lshl_add_u64 v[214:215], v[214:215], 0, s[96:97]
	s_mov_b32 m0, s27
	ds_read_b128 v[166:169], v246 offset:49152
	ds_read_b128 v[170:173], v246 offset:50176
	ds_read_b128 v[174:177], v246 offset:51200
	ds_read_b128 v[178:181], v246 offset:52224
	ds_read_b128 v[182:185], v246 offset:53248
	ds_read_b128 v[186:189], v246 offset:54272
	ds_read_b128 v[190:193], v246 offset:55296
	ds_read_b128 v[210:213], v246 offset:56320
	global_load_lds_dwordx4 v[214:215], off
	v_lshl_add_u64 v[214:215], v[216:217], 0, s[96:97]
	s_add_i32 m0, s27, 0x2000
	s_add_i32 s27, s46, s55
	global_load_lds_dwordx4 v[214:215], off
	v_lshl_add_u64 v[214:215], v[218:219], 0, s[96:97]
	s_mov_b32 m0, s27
	s_nop 0
	global_load_lds_dwordx4 v[214:215], off
	v_lshl_add_u64 v[214:215], v[220:221], 0, s[96:97]
	s_add_i32 m0, s27, 0x2000
	s_nop 0
	global_load_lds_dwordx4 v[214:215], off
	v_lshl_add_u64 v[214:215], s[10:11], 0, v[200:201]
	s_mov_b32 m0, s63
	s_nop 0
	global_load_lds_dwordx4 v[214:215], off
	v_lshl_add_u64 v[214:215], s[10:11], 0, v[196:197]
	s_mov_b32 m0, s64
	s_nop 0
	global_load_lds_dwordx4 v[214:215], off
	s_add_u32 s0, s0, 0x100
	s_addc_u32 s1, s1, 0
	s_cmp_ge_u32 s23, s94
	s_mov_b32 s10, s23
	s_cbranch_scc1 .Lrot0_skip
	s_or_b32 s11, s10, 1
	s_cmp_ge_u32 s11, s84
	s_cselect_b32 s27, s86, 0
	s_cselect_b32 s79, s85, 0
	s_add_i32 s23, s10, 2
	s_cmp_ge_u32 s23, s84
	s_cselect_b32 s44, s86, 0
	s_cselect_b32 s11, s85, 0
	s_add_u32 s44, s44, s0
	s_addc_u32 s11, s11, s1
	s_add_u32 s44, s2, s44
	s_addc_u32 s11, s3, s11
	s_add_u32 s44, s44, 0x100
	s_addc_u32 s11, s11, 0
	s_add_u32 s46, s20, s0
	s_addc_u32 s47, s21, s1
	s_add_i32 s10, s10, 3
	s_cmp_ge_u32 s10, s84
	s_cselect_b32 s45, s86, 0
	s_cselect_b32 s10, s85, 0
	s_add_u32 s45, s45, s0
	s_addc_u32 s10, s10, s1
	s_add_u32 s45, s2, s45
	s_addc_u32 s10, s3, s10
	s_add_u32 s78, s45, 0x180
	s_addc_u32 s10, s10, 0
	s_cmp_eq_u32 s22, s0
	s_cselect_b32 s45, s41, s11
	s_cselect_b32 s44, s40, s44
	s_cselect_b32 s47, s43, s47
	s_cselect_b32 s46, s42, s46
	s_cselect_b32 s11, s19, s10
	s_cselect_b32 s10, s18, s78
	s_cmp_lg_u32 s0, s0
.Lrot0_skip:
	s_waitcnt vmcnt(8)
	s_waitcnt lgkmcnt(0)
	s_barrier
	s_setprio 1
	s_waitcnt lgkmcnt(0)
	v_mfma_f32_16x16x32_bf16 v[58:61], v[134:137], v[166:169], v[58:61]
	v_mfma_f32_16x16x32_bf16 v[50:53], v[142:145], v[166:169], v[50:53]
	v_mfma_f32_16x16x32_bf16 v[42:45], v[134:137], v[174:177], v[42:45]
	v_mfma_f32_16x16x32_bf16 v[34:37], v[142:145], v[174:177], v[34:37]
	v_mfma_f32_16x16x32_bf16 v[26:29], v[134:137], v[182:185], v[26:29]
	v_mfma_f32_16x16x32_bf16 v[18:21], v[142:145], v[182:185], v[18:21]
	v_mfma_f32_16x16x32_bf16 v[10:13], v[134:137], v[190:193], v[10:13]
	v_mfma_f32_16x16x32_bf16 v[6:9], v[142:145], v[190:193], v[6:9]
	v_mfma_f32_16x16x32_bf16 v[58:61], v[138:141], v[170:173], v[58:61]
	v_mfma_f32_16x16x32_bf16 v[50:53], v[146:149], v[170:173], v[50:53]
	v_mfma_f32_16x16x32_bf16 v[42:45], v[138:141], v[178:181], v[42:45]
	v_mfma_f32_16x16x32_bf16 v[34:37], v[146:149], v[178:181], v[34:37]
	v_mfma_f32_16x16x32_bf16 v[26:29], v[138:141], v[186:189], v[26:29]
	v_mfma_f32_16x16x32_bf16 v[18:21], v[146:149], v[186:189], v[18:21]
	v_mfma_f32_16x16x32_bf16 v[10:13], v[138:141], v[210:213], v[10:13]
	v_mfma_f32_16x16x32_bf16 v[6:9], v[146:149], v[210:213], v[6:9]
	s_setprio 0
	s_setprio 1
	v_mfma_f32_16x16x32_bf16 v[62:65], v[150:153], v[166:169], v[62:65]
	v_mfma_f32_16x16x32_bf16 v[54:57], v[158:161], v[166:169], v[54:57]
	v_mfma_f32_16x16x32_bf16 v[46:49], v[150:153], v[174:177], v[46:49]
	v_mfma_f32_16x16x32_bf16 v[38:41], v[158:161], v[174:177], v[38:41]
	v_mfma_f32_16x16x32_bf16 v[30:33], v[150:153], v[182:185], v[30:33]
	v_mfma_f32_16x16x32_bf16 v[22:25], v[158:161], v[182:185], v[22:25]
	v_mfma_f32_16x16x32_bf16 v[14:17], v[150:153], v[190:193], v[14:17]
	v_mfma_f32_16x16x32_bf16 v[2:5], v[158:161], v[190:193], v[2:5]
	v_mfma_f32_16x16x32_bf16 v[62:65], v[154:157], v[170:173], v[62:65]
	v_mfma_f32_16x16x32_bf16 v[54:57], v[162:165], v[170:173], v[54:57]
	v_mfma_f32_16x16x32_bf16 v[46:49], v[154:157], v[178:181], v[46:49]
	v_mfma_f32_16x16x32_bf16 v[38:41], v[162:165], v[178:181], v[38:41]
	v_mfma_f32_16x16x32_bf16 v[30:33], v[154:157], v[186:189], v[30:33]
	v_mfma_f32_16x16x32_bf16 v[22:25], v[162:165], v[186:189], v[22:25]
	v_mfma_f32_16x16x32_bf16 v[14:17], v[154:157], v[210:213], v[14:17]
	v_mfma_f32_16x16x32_bf16 v[2:5], v[162:165], v[210:213], v[2:5]
	s_setprio 0
	s_barrier
	s_cbranch_scc0 .Lrot0_body
	v_readlane_b32 s90, v254, 43
	v_readlane_b32 s91, v254, 44
	s_and_b64 vcc, exec, s[34:35]
	s_cbranch_vccz .LBB0_609

; #define PG8_STAGE(bufoff, gbase, voff) do { _Pragma("unroll") for (int _i = 0; _i < 2; ++_i) \
;         __builtin_amdgcn_global_load_lds((const unsigned*)((const char*)(gbase) + (voff)[_i]), (PG8_LAS unsigned*)(lds + (bufoff) + ldsw + _i * 8192), 16, 0, 0); } while (0)
; #define PG8_LDA(dst, b, h) do { _Pragma("unroll") for (int m = 0; m < 4; ++m) _Pragma("unroll") for (int k = 0; k < 2; ++k) dst[m][k] = *(const PG8_LAS bf16x8*)(lds + PG8_SA(b, h) + aoff + m * 2048 + k * 1024); } while (0)
; #define PG8_LDB(dst, b, h) do { _Pragma("unroll") for (int n = 0; n < 2; ++n) _Pragma("unroll") for (int k = 0; k < 2; ++k) dst[n][k] = *(const PG8_LAS bf16x8*)(lds + PG8_SB(b, h) + boff + n * 2048 + k * 1024); } while (0)
; #define PG8_MMA(ai, bj, At, Bt) do { __builtin_amdgcn_s_setprio(1); _Pragma("unroll") for (int m = 0; m < 4; ++m) _Pragma("unroll") for (int n = 0; n < 2; ++n) _Pragma("unroll") for (int k = 0; k < 2; ++k) \
;         acc[ai][bj][m][n] = __builtin_amdgcn_mfma_f32_16x16x32_bf16(Bt[n][k], At[m][k], acc[ai][bj][m][n], 0, 0, 0); __builtin_amdgcn_s_setprio(0); } while (0)
; #define PG8_WAIT_V(n) asm volatile("s_waitcnt vmcnt(" #n ")" ::: "memory")
; #define PG8_WAIT_L(n) asm volatile("s_waitcnt lgkmcnt(" #n ")" ::: "memory")
; #define PG8_BAR __builtin_amdgcn_s_barrier()
; #define PG8_SCHED __builtin_amdgcn_sched_barrier(0)
; template <class Epi, class Sched, bool ALIGN_EPI = false, bool SP2 = false>
; __device__ __forceinline__ void gemm_phase(PG8_LAS unsigned char* lds, const Gemm g, const Sched& S, const Epi& E, int tid_in) {
;     ...
;             PG8_LDB(B0, 0, 0); PG8_LDB(B1, 0, 1); PG8_SCHED; PG8_LDA(At, 0, 0); PG8_STAGE(PG8_SA(1, 1), a1 + hstepA, voffA);
;             PG8_WAIT_V(8); PG8_WAIT_L(0); PG8_BAR; PG8_MMA(0, 0, At, B0); PG8_MMA(0, 1, At, B1); PG8_BAR; PG8_SCHED;
;             PG8_LDA(At, 0, 1); PG8_STAGE(PG8_SB(0, 0), b2, voffB); PG8_STAGE(PG8_SB(0, 1), b2 + hstep, voffB); PG8_STAGE(PG8_SA(0, 0), a2, voffA);
.Lrot1_body:
	s_add_i32 s62, 0, 0x10000
	v_add_u32_e32 v0, s62, v207
	s_add_i32 s63, 0, 0x14000
	ds_read_b128 v[132:135], v0
	ds_read_b128 v[136:139], v0 offset:1024
	ds_read_b128 v[140:143], v0 offset:2048
	ds_read_b128 v[144:147], v0 offset:3072
	v_add_u32_e32 v0, s63, v207
	ds_read_b128 v[148:151], v0
	ds_read_b128 v[152:155], v0 offset:1024
	ds_read_b128 v[156:159], v0 offset:2048
	ds_read_b128 v[160:163], v0 offset:3072
	v_lshl_add_u64 v[2:3], s[6:7], 0, v[180:181]
	v_lshl_add_u64 v[2:3], v[2:3], 0, s[58:59]
	s_add_i32 m0, s89, 0xc000
	ds_read_b128 v[164:167], v208
	ds_read_b128 v[168:171], v208 offset:1024
	ds_read_b128 v[184:187], v208 offset:2048
	ds_read_b128 v[188:191], v208 offset:3072
	ds_read_b128 v[196:199], v208 offset:4096
	ds_read_b128 v[200:203], v208 offset:5120
	ds_read_b128 v[210:213], v208 offset:6144
	ds_read_b128 v[214:217], v208 offset:7168
	global_load_lds_dwordx4 v[2:3], off
	v_lshl_add_u64 v[2:3], s[6:7], 0, v[182:183]
	v_lshl_add_u64 v[2:3], v[2:3], 0, s[58:59]
	s_add_i32 m0, s89, 0xe000
	s_nop 0
	global_load_lds_dwordx4 v[2:3], off
	s_waitcnt vmcnt(8)
	s_waitcnt lgkmcnt(0)
	s_barrier
	s_setprio 1
	s_waitcnt lgkmcnt(0)
	v_mfma_f32_16x16x32_bf16 v[124:127], v[132:135], v[164:167], v[124:127]
	v_mfma_f32_16x16x32_bf16 v[116:119], v[140:143], v[164:167], v[116:119]
	v_mfma_f32_16x16x32_bf16 v[108:111], v[132:135], v[184:187], v[108:111]
	v_mfma_f32_16x16x32_bf16 v[100:103], v[140:143], v[184:187], v[100:103]
	v_mfma_f32_16x16x32_bf16 v[92:95], v[132:135], v[196:199], v[92:95]
	v_mfma_f32_16x16x32_bf16 v[84:87], v[140:143], v[196:199], v[84:87]
	v_mfma_f32_16x16x32_bf16 v[76:79], v[132:135], v[210:213], v[76:79]
	v_mfma_f32_16x16x32_bf16 v[68:71], v[140:143], v[210:213], v[68:71]
	v_mfma_f32_16x16x32_bf16 v[124:127], v[136:139], v[168:171], v[124:127]
	v_mfma_f32_16x16x32_bf16 v[116:119], v[144:147], v[168:171], v[116:119]
	v_mfma_f32_16x16x32_bf16 v[108:111], v[136:139], v[188:191], v[108:111]
	v_mfma_f32_16x16x32_bf16 v[100:103], v[144:147], v[188:191], v[100:103]
	v_mfma_f32_16x16x32_bf16 v[92:95], v[136:139], v[200:203], v[92:95]
	v_mfma_f32_16x16x32_bf16 v[84:87], v[144:147], v[200:203], v[84:87]
	v_mfma_f32_16x16x32_bf16 v[76:79], v[136:139], v[214:217], v[76:79]
	v_mfma_f32_16x16x32_bf16 v[68:71], v[144:147], v[214:217], v[68:71]
	s_setprio 0
	s_setprio 1
	v_mfma_f32_16x16x32_bf16 v[128:131], v[148:151], v[164:167], v[128:131]
	v_mfma_f32_16x16x32_bf16 v[120:123], v[156:159], v[164:167], v[120:123]
	v_mfma_f32_16x16x32_bf16 v[112:115], v[148:151], v[184:187], v[112:115]
	v_mfma_f32_16x16x32_bf16 v[104:107], v[156:159], v[184:187], v[104:107]
	v_mfma_f32_16x16x32_bf16 v[96:99], v[148:151], v[196:199], v[96:99]
	v_mfma_f32_16x16x32_bf16 v[88:91], v[156:159], v[196:199], v[88:91]
	v_mfma_f32_16x16x32_bf16 v[80:83], v[148:151], v[210:213], v[80:83]
	v_mfma_f32_16x16x32_bf16 v[72:75], v[156:159], v[210:213], v[72:75]
	v_mfma_f32_16x16x32_bf16 v[128:131], v[152:155], v[168:171], v[128:131]
	v_mfma_f32_16x16x32_bf16 v[120:123], v[160:163], v[168:171], v[120:123]
	v_mfma_f32_16x16x32_bf16 v[112:115], v[152:155], v[188:191], v[112:115]
	v_mfma_f32_16x16x32_bf16 v[104:107], v[160:163], v[188:191], v[104:107]
	v_mfma_f32_16x16x32_bf16 v[96:99], v[152:155], v[200:203], v[96:99]
	v_mfma_f32_16x16x32_bf16 v[88:91], v[160:163], v[200:203], v[88:91]
	v_mfma_f32_16x16x32_bf16 v[80:83], v[152:155], v[214:217], v[80:83]
	v_mfma_f32_16x16x32_bf16 v[72:75], v[160:163], v[214:217], v[72:75]
	s_setprio 0
	s_barrier
	s_add_i32 s58, s62, s88
	v_lshl_add_u64 v[192:193], s[60:61], 0, v[178:179]
	s_mov_b32 m0, s58
	ds_read_b128 v[164:167], v208 offset:16384
	ds_read_b128 v[168:171], v208 offset:17408
	ds_read_b128 v[184:187], v208 offset:18432
	ds_read_b128 v[188:191], v208 offset:19456
	ds_read_b128 v[196:199], v208 offset:20480
	ds_read_b128 v[200:203], v208 offset:21504
	ds_read_b128 v[210:213], v208 offset:22528
	ds_read_b128 v[214:217], v208 offset:23552
	global_load_lds_dwordx4 v[192:193], off
	s_add_i32 m0, s58, 0x2000
	s_add_u32 s58, s60, s94
	v_lshl_add_u64 v[204:205], s[60:61], 0, v[174:175]
	s_addc_u32 s59, s61, 0
	s_add_i32 s60, s63, s88
	global_load_lds_dwordx4 v[204:205], off
	v_lshl_add_u64 v[218:219], s[58:59], 0, v[178:179]
	s_mov_b32 m0, s60
	v_lshl_add_u64 v[220:221], s[58:59], 0, v[174:175]
	global_load_lds_dwordx4 v[218:219], off
	s_add_i32 m0, s60, 0x2000
	v_lshl_add_u64 v[2:3], s[8:9], 0, v[176:177]
	global_load_lds_dwordx4 v[220:221], off
	s_mov_b32 m0, s89
	s_nop 0
	global_load_lds_dwordx4 v[2:3], off
	v_lshl_add_u64 v[2:3], s[8:9], 0, v[172:173]
	s_mov_b32 m0, s90
	s_nop 0
	global_load_lds_dwordx4 v[2:3], off
	s_waitcnt vmcnt(8)
	s_waitcnt lgkmcnt(0)
	s_barrier
; #define PG8_STAGE(bufoff, gbase, voff) do { _Pragma("unroll") for (int _i = 0; _i < 2; ++_i) \
;         __builtin_amdgcn_global_load_lds((const unsigned*)((const char*)(gbase) + (voff)[_i]), (PG8_LAS unsigned*)(lds + (bufoff) + ldsw + _i * 8192), 16, 0, 0); } while (0)
; #define PG8_LDA(dst, b, h) do { _Pragma("unroll") for (int m = 0; m < 4; ++m) _Pragma("unroll") for (int k = 0; k < 2; ++k) dst[m][k] = *(const PG8_LAS bf16x8*)(lds + PG8_SA(b, h) + aoff + m * 2048 + k * 1024); } while (0)
; #define PG8_LDB(dst, b, h) do { _Pragma("unroll") for (int n = 0; n < 2; ++n) _Pragma("unroll") for (int k = 0; k < 2; ++k) dst[n][k] = *(const PG8_LAS bf16x8*)(lds + PG8_SB(b, h) + boff + n * 2048 + k * 1024); } while (0)
; #define PG8_MMA(ai, bj, At, Bt) do { __builtin_amdgcn_s_setprio(1); _Pragma("unroll") for (int m = 0; m < 4; ++m) _Pragma("unroll") for (int n = 0; n < 2; ++n) _Pragma("unroll") for (int k = 0; k < 2; ++k) \
;         acc[ai][bj][m][n] = __builtin_amdgcn_mfma_f32_16x16x32_bf16(Bt[n][k], At[m][k], acc[ai][bj][m][n], 0, 0, 0); __builtin_amdgcn_s_setprio(0); } while (0)
; #define PG8_WAIT_V(n) asm volatile("s_waitcnt vmcnt(" #n ")" ::: "memory")
; #define PG8_WAIT_L(n) asm volatile("s_waitcnt lgkmcnt(" #n ")" ::: "memory")
; #define PG8_BAR __builtin_amdgcn_s_barrier()
; #define PG8_SCHED __builtin_amdgcn_sched_barrier(0)
; template <class Epi, class Sched, bool ALIGN_EPI = false, bool SP2 = false>
; __device__ __forceinline__ void gemm_phase(PG8_LAS unsigned char* lds, const Gemm g, const Sched& S, const Epi& E, int tid_in) {
;     ...
;             PG8_WAIT_V(8); PG8_WAIT_L(0); PG8_BAR; PG8_MMA(1, 0, At, B0); PG8_MMA(1, 1, At, B1); PG8_BAR; PG8_SCHED;
;             PG8_LDB(B0, 1, 0); PG8_LDB(B1, 1, 1); PG8_SCHED; PG8_LDA(At, 1, 0); PG8_STAGE(PG8_SA(0, 1), a2 + hstepA, voffA);
;             PG8_WAIT_V(8); PG8_WAIT_L(0); PG8_BAR; PG8_MMA(0, 0, At, B0); PG8_MMA(0, 1, At, B1); PG8_BAR; PG8_SCHED;
	s_setprio 1
	s_waitcnt lgkmcnt(0)
	v_mfma_f32_16x16x32_bf16 v[60:63], v[132:135], v[164:167], v[60:63]
	v_mfma_f32_16x16x32_bf16 v[52:55], v[140:143], v[164:167], v[52:55]
	v_mfma_f32_16x16x32_bf16 v[44:47], v[132:135], v[184:187], v[44:47]
	v_mfma_f32_16x16x32_bf16 v[36:39], v[140:143], v[184:187], v[36:39]
	v_mfma_f32_16x16x32_bf16 v[28:31], v[132:135], v[196:199], v[28:31]
	v_mfma_f32_16x16x32_bf16 v[20:23], v[140:143], v[196:199], v[20:23]
	v_mfma_f32_16x16x32_bf16 v[12:15], v[132:135], v[210:213], v[12:15]
	v_mfma_f32_16x16x32_bf16 v[2:5], v[140:143], v[210:213], v[4:7]
	v_mfma_f32_16x16x32_bf16 v[60:63], v[136:139], v[168:171], v[60:63]
	v_mfma_f32_16x16x32_bf16 v[52:55], v[144:147], v[168:171], v[52:55]
	v_mfma_f32_16x16x32_bf16 v[44:47], v[136:139], v[188:191], v[44:47]
	v_mfma_f32_16x16x32_bf16 v[36:39], v[144:147], v[188:191], v[36:39]
	v_mfma_f32_16x16x32_bf16 v[28:31], v[136:139], v[200:203], v[28:31]
	v_mfma_f32_16x16x32_bf16 v[20:23], v[144:147], v[200:203], v[20:23]
	v_mfma_f32_16x16x32_bf16 v[12:15], v[136:139], v[214:217], v[12:15]
	v_mfma_f32_16x16x32_bf16 v[2:5], v[144:147], v[214:217], v[2:5]
	s_setprio 0
	s_setprio 1
	v_mfma_f32_16x16x32_bf16 v[64:67], v[148:151], v[164:167], v[64:67]
	v_mfma_f32_16x16x32_bf16 v[56:59], v[156:159], v[164:167], v[56:59]
	v_mfma_f32_16x16x32_bf16 v[48:51], v[148:151], v[184:187], v[48:51]
	v_mfma_f32_16x16x32_bf16 v[40:43], v[156:159], v[184:187], v[40:43]
	v_mfma_f32_16x16x32_bf16 v[32:35], v[148:151], v[196:199], v[32:35]
	v_mfma_f32_16x16x32_bf16 v[24:27], v[156:159], v[196:199], v[24:27]
	v_mfma_f32_16x16x32_bf16 v[16:19], v[148:151], v[210:213], v[16:19]
	v_mfma_f32_16x16x32_bf16 v[6:9], v[156:159], v[210:213], v[8:11]
	v_mfma_f32_16x16x32_bf16 v[64:67], v[152:155], v[168:171], v[64:67]
	v_mfma_f32_16x16x32_bf16 v[56:59], v[160:163], v[168:171], v[56:59]
	v_mfma_f32_16x16x32_bf16 v[48:51], v[152:155], v[188:191], v[48:51]
	v_mfma_f32_16x16x32_bf16 v[40:43], v[160:163], v[188:191], v[40:43]
	v_mfma_f32_16x16x32_bf16 v[32:35], v[152:155], v[200:203], v[32:35]
	v_mfma_f32_16x16x32_bf16 v[24:27], v[160:163], v[200:203], v[24:27]
	v_mfma_f32_16x16x32_bf16 v[16:19], v[152:155], v[214:217], v[16:19]
	v_mfma_f32_16x16x32_bf16 v[8:11], v[160:163], v[214:217], v[6:9]
	s_setprio 0
	s_barrier
	s_add_i32 s58, 0, 0x18000
	v_add_u32_e32 v0, s58, v207
	s_add_i32 s59, 0, 0x1c000
	ds_read_b128 v[132:135], v0
	ds_read_b128 v[136:139], v0 offset:1024
	ds_read_b128 v[140:143], v0 offset:2048
	ds_read_b128 v[144:147], v0 offset:3072
	v_add_u32_e32 v0, s59, v207
	ds_read_b128 v[148:151], v0
	ds_read_b128 v[152:155], v0 offset:1024
	ds_read_b128 v[156:159], v0 offset:2048
	ds_read_b128 v[160:163], v0 offset:3072
	s_add_u32 s8, s8, s94
	s_addc_u32 s9, s9, 0
	s_mov_b32 m0, s91
	v_lshl_add_u64 v[6:7], s[8:9], 0, v[176:177]
	ds_read_b128 v[164:167], v208 offset:32768
	ds_read_b128 v[168:171], v208 offset:33792
	ds_read_b128 v[184:187], v208 offset:34816
	ds_read_b128 v[188:191], v208 offset:35840
	ds_read_b128 v[196:199], v208 offset:36864
	ds_read_b128 v[200:203], v208 offset:37888
	ds_read_b128 v[210:213], v208 offset:38912
	ds_read_b128 v[214:217], v208 offset:39936
	global_load_lds_dwordx4 v[6:7], off
	v_lshl_add_u64 v[6:7], s[8:9], 0, v[172:173]
	s_mov_b32 m0, s92
	s_nop 0
	global_load_lds_dwordx4 v[6:7], off
	s_waitcnt vmcnt(8)
	s_waitcnt lgkmcnt(0)
	s_barrier
	s_setprio 1
	s_waitcnt lgkmcnt(0)
	v_mfma_f32_16x16x32_bf16 v[124:127], v[132:135], v[164:167], v[124:127]
	v_mfma_f32_16x16x32_bf16 v[116:119], v[140:143], v[164:167], v[116:119]
	v_mfma_f32_16x16x32_bf16 v[108:111], v[132:135], v[184:187], v[108:111]
	v_mfma_f32_16x16x32_bf16 v[100:103], v[140:143], v[184:187], v[100:103]
	v_mfma_f32_16x16x32_bf16 v[92:95], v[132:135], v[196:199], v[92:95]
	v_mfma_f32_16x16x32_bf16 v[84:87], v[140:143], v[196:199], v[84:87]
	v_mfma_f32_16x16x32_bf16 v[76:79], v[132:135], v[210:213], v[76:79]
	v_mfma_f32_16x16x32_bf16 v[68:71], v[140:143], v[210:213], v[68:71]
	v_mfma_f32_16x16x32_bf16 v[124:127], v[136:139], v[168:171], v[124:127]
	v_mfma_f32_16x16x32_bf16 v[116:119], v[144:147], v[168:171], v[116:119]
	v_mfma_f32_16x16x32_bf16 v[108:111], v[136:139], v[188:191], v[108:111]
	v_mfma_f32_16x16x32_bf16 v[100:103], v[144:147], v[188:191], v[100:103]
	v_mfma_f32_16x16x32_bf16 v[92:95], v[136:139], v[200:203], v[92:95]
	v_mfma_f32_16x16x32_bf16 v[84:87], v[144:147], v[200:203], v[84:87]
	v_mfma_f32_16x16x32_bf16 v[76:79], v[136:139], v[214:217], v[76:79]
	v_mfma_f32_16x16x32_bf16 v[68:71], v[144:147], v[214:217], v[68:71]
	s_setprio 0
	s_setprio 1
	v_mfma_f32_16x16x32_bf16 v[128:131], v[148:151], v[164:167], v[128:131]
	v_mfma_f32_16x16x32_bf16 v[120:123], v[156:159], v[164:167], v[120:123]
	v_mfma_f32_16x16x32_bf16 v[112:115], v[148:151], v[184:187], v[112:115]
	v_mfma_f32_16x16x32_bf16 v[104:107], v[156:159], v[184:187], v[104:107]
	v_mfma_f32_16x16x32_bf16 v[96:99], v[148:151], v[196:199], v[96:99]
	v_mfma_f32_16x16x32_bf16 v[88:91], v[156:159], v[196:199], v[88:91]
	v_mfma_f32_16x16x32_bf16 v[80:83], v[148:151], v[210:213], v[80:83]
	v_mfma_f32_16x16x32_bf16 v[72:75], v[156:159], v[210:213], v[72:75]
	v_mfma_f32_16x16x32_bf16 v[128:131], v[152:155], v[168:171], v[128:131]
	v_mfma_f32_16x16x32_bf16 v[120:123], v[160:163], v[168:171], v[120:123]
	v_mfma_f32_16x16x32_bf16 v[112:115], v[152:155], v[188:191], v[112:115]
	v_mfma_f32_16x16x32_bf16 v[104:107], v[160:163], v[188:191], v[104:107]
	v_mfma_f32_16x16x32_bf16 v[96:99], v[152:155], v[200:203], v[96:99]
	v_mfma_f32_16x16x32_bf16 v[88:91], v[160:163], v[200:203], v[88:91]
	v_mfma_f32_16x16x32_bf16 v[80:83], v[152:155], v[214:217], v[80:83]
	v_mfma_f32_16x16x32_bf16 v[72:75], v[160:163], v[214:217], v[72:75]
	s_setprio 0
	s_barrier
; #define PG8_STAGE(bufoff, gbase, voff) do { _Pragma("unroll") for (int _i = 0; _i < 2; ++_i) \
;         __builtin_amdgcn_global_load_lds((const unsigned*)((const char*)(gbase) + (voff)[_i]), (PG8_LAS unsigned*)(lds + (bufoff) + ldsw + _i * 8192), 16, 0, 0); } while (0)
; #define PG8_LDA(dst, b, h) do { _Pragma("unroll") for (int m = 0; m < 4; ++m) _Pragma("unroll") for (int k = 0; k < 2; ++k) dst[m][k] = *(const PG8_LAS bf16x8*)(lds + PG8_SA(b, h) + aoff + m * 2048 + k * 1024); } while (0)
; #define PG8_MMA(ai, bj, At, Bt) do { __builtin_amdgcn_s_setprio(1); _Pragma("unroll") for (int m = 0; m < 4; ++m) _Pragma("unroll") for (int n = 0; n < 2; ++n) _Pragma("unroll") for (int k = 0; k < 2; ++k) \
;         acc[ai][bj][m][n] = __builtin_amdgcn_mfma_f32_16x16x32_bf16(Bt[n][k], At[m][k], acc[ai][bj][m][n], 0, 0, 0); __builtin_amdgcn_s_setprio(0); } while (0)
; #define PG8_WAIT_V(n) asm volatile("s_waitcnt vmcnt(" #n ")" ::: "memory")
; #define PG8_WAIT_L(n) asm volatile("s_waitcnt lgkmcnt(" #n ")" ::: "memory")
; #define PG8_BAR __builtin_amdgcn_s_barrier()
; #define PG8_SCHED __builtin_amdgcn_sched_barrier(0)
; template <class Epi, class Sched, bool ALIGN_EPI = false, bool SP2 = false>
; __device__ __forceinline__ void gemm_phase(PG8_LAS unsigned char* lds, const Gemm g, const Sched& S, const Epi& E, int tid_in) {
;     ...
;         for (int t = 0; t < ntc; t += 2) {
;             const bool last = (t == ntc - 2);
;             const char* a1 = PG8_KA(cA, t + 1);
;             const char* a2 = last ? nA : PG8_KA(cA, t + 2); const char* b2 = last ? nB : cB + (size_t)(t + 2) * kstep;
;             const char* a3 = last ? PG8_KA(nA, 1) : PG8_KA(cA, t + 3); const char* b3 = b2 + kstep;
;     ...
;             PG8_LDA(At, 1, 1); PG8_STAGE(PG8_SB(1, 0), b3, voffB); PG8_STAGE(PG8_SB(1, 1), b3 + hstep, voffB); PG8_STAGE(PG8_SA(1, 0), a3, voffA);
;             PG8_WAIT_V(8); PG8_WAIT_L(0); PG8_BAR; PG8_MMA(1, 0, At, B0); PG8_MMA(1, 1, At, B1); PG8_BAR; PG8_SCHED;
	s_add_i32 s8, s58, s88
	v_lshl_add_u64 v[6:7], v[192:193], 0, s[96:97]
	s_mov_b32 m0, s8
	ds_read_b128 v[164:167], v208 offset:49152
	ds_read_b128 v[168:171], v208 offset:50176
	ds_read_b128 v[184:187], v208 offset:51200
	ds_read_b128 v[188:191], v208 offset:52224
	ds_read_b128 v[196:199], v208 offset:53248
	ds_read_b128 v[200:203], v208 offset:54272
	ds_read_b128 v[210:213], v208 offset:55296
	ds_read_b128 v[214:217], v208 offset:56320
	global_load_lds_dwordx4 v[6:7], off
	v_lshl_add_u64 v[6:7], v[204:205], 0, s[96:97]
	s_add_i32 m0, s8, 0x2000
	s_add_i32 s8, s59, s88
	global_load_lds_dwordx4 v[6:7], off
	v_lshl_add_u64 v[6:7], v[218:219], 0, s[96:97]
	s_mov_b32 m0, s8
	s_nop 0
	global_load_lds_dwordx4 v[6:7], off
	v_lshl_add_u64 v[6:7], v[220:221], 0, s[96:97]
	s_add_i32 m0, s8, 0x2000
	s_nop 0
	global_load_lds_dwordx4 v[6:7], off
	v_lshl_add_u64 v[6:7], s[0:1], 0, v[176:177]
	s_mov_b32 m0, s93
	s_nop 0
	global_load_lds_dwordx4 v[6:7], off
	v_lshl_add_u64 v[6:7], s[0:1], 0, v[172:173]
	s_mov_b32 m0, s78
	s_nop 0
	global_load_lds_dwordx4 v[6:7], off
	s_add_u32 s6, s6, 0x100
	s_addc_u32 s7, s7, 0
	s_add_u32 s54, s54, 0x100
	s_addc_u32 s55, s55, 0
	s_add_i32 s56, s56, -2
	s_cmp_ge_u32 s57, s18
	s_mov_b32 s0, s57
	s_cbranch_scc1 .Lrot1_skip
	s_or_b32 s1, s0, 1
	s_cmp_ge_u32 s1, s84
	s_cselect_b32 s58, s86, 0
	s_cselect_b32 s59, s85, 0
	s_add_i32 s57, s0, 2
	s_cmp_ge_u32 s57, s84
	s_cselect_b32 s8, s86, 0
	s_cselect_b32 s1, s85, 0
	s_add_u32 s8, s6, s8
	s_addc_u32 s1, s7, s1
	s_add_u32 s8, s8, 0x100
	s_addc_u32 s1, s1, 0
	s_add_i32 s0, s0, 3
	s_cmp_ge_u32 s0, s84
	s_cselect_b32 s9, s86, 0
	s_cselect_b32 s0, s85, 0
	s_add_u32 s9, s6, s9
	s_addc_u32 s0, s7, s0
	s_add_u32 s62, s9, 0x180
	s_addc_u32 s0, s0, 0
	s_cmp_eq_u32 s56, 0
	s_cselect_b32 s9, s49, s1
	s_cselect_b32 s8, s48, s8
	s_cselect_b32 s61, s51, s55
	s_cselect_b32 s60, s50, s54
	s_cselect_b32 s1, s53, s0
	s_cselect_b32 s0, s21, s62
	s_cmp_lg_u32 s6, s6
.Lrot1_skip:
	s_waitcnt vmcnt(8)
	s_waitcnt lgkmcnt(0)
	s_barrier
	s_setprio 1
	s_waitcnt lgkmcnt(0)
	v_mfma_f32_16x16x32_bf16 v[60:63], v[132:135], v[164:167], v[60:63]
	v_mfma_f32_16x16x32_bf16 v[52:55], v[140:143], v[164:167], v[52:55]
	v_mfma_f32_16x16x32_bf16 v[44:47], v[132:135], v[184:187], v[44:47]
	v_mfma_f32_16x16x32_bf16 v[36:39], v[140:143], v[184:187], v[36:39]
	v_mfma_f32_16x16x32_bf16 v[28:31], v[132:135], v[196:199], v[28:31]
	v_mfma_f32_16x16x32_bf16 v[20:23], v[140:143], v[196:199], v[20:23]
	v_mfma_f32_16x16x32_bf16 v[12:15], v[132:135], v[210:213], v[12:15]
	v_mfma_f32_16x16x32_bf16 v[2:5], v[140:143], v[210:213], v[2:5]
	v_mfma_f32_16x16x32_bf16 v[60:63], v[136:139], v[168:171], v[60:63]
	v_mfma_f32_16x16x32_bf16 v[52:55], v[144:147], v[168:171], v[52:55]
	v_mfma_f32_16x16x32_bf16 v[44:47], v[136:139], v[188:191], v[44:47]
	v_mfma_f32_16x16x32_bf16 v[36:39], v[144:147], v[188:191], v[36:39]
	v_mfma_f32_16x16x32_bf16 v[28:31], v[136:139], v[200:203], v[28:31]
	v_mfma_f32_16x16x32_bf16 v[20:23], v[144:147], v[200:203], v[20:23]
	v_mfma_f32_16x16x32_bf16 v[12:15], v[136:139], v[214:217], v[12:15]
	v_mfma_f32_16x16x32_bf16 v[4:7], v[144:147], v[214:217], v[2:5]
	s_setprio 0
	s_setprio 1
	v_mfma_f32_16x16x32_bf16 v[64:67], v[148:151], v[164:167], v[64:67]
	v_mfma_f32_16x16x32_bf16 v[56:59], v[156:159], v[164:167], v[56:59]
	v_mfma_f32_16x16x32_bf16 v[48:51], v[148:151], v[184:187], v[48:51]
	v_mfma_f32_16x16x32_bf16 v[40:43], v[156:159], v[184:187], v[40:43]
	v_mfma_f32_16x16x32_bf16 v[32:35], v[148:151], v[196:199], v[32:35]
	v_mfma_f32_16x16x32_bf16 v[24:27], v[156:159], v[196:199], v[24:27]
	v_mfma_f32_16x16x32_bf16 v[16:19], v[148:151], v[210:213], v[16:19]
	v_mfma_f32_16x16x32_bf16 v[8:11], v[156:159], v[210:213], v[8:11]
	v_mfma_f32_16x16x32_bf16 v[64:67], v[152:155], v[168:171], v[64:67]
	v_mfma_f32_16x16x32_bf16 v[56:59], v[160:163], v[168:171], v[56:59]
	v_mfma_f32_16x16x32_bf16 v[48:51], v[152:155], v[188:191], v[48:51]
	v_mfma_f32_16x16x32_bf16 v[40:43], v[160:163], v[188:191], v[40:43]
	v_mfma_f32_16x16x32_bf16 v[32:35], v[152:155], v[200:203], v[32:35]
	v_mfma_f32_16x16x32_bf16 v[24:27], v[160:163], v[200:203], v[24:27]
	v_mfma_f32_16x16x32_bf16 v[16:19], v[152:155], v[214:217], v[16:19]
	v_mfma_f32_16x16x32_bf16 v[8:11], v[160:163], v[214:217], v[8:11]
	s_setprio 0
	s_barrier
	s_cbranch_scc0 .Lrot1_body
	s_and_b64 vcc, exec, s[76:77]
	s_cbranch_vccz .LBB0_1183
	s_barrier
